# diff-attn: Q-fragment vmcnt waits hoisted out of tile loop; scan pass1 loads batched/pipelined
# speedup vs baseline: 1.0293x; 1.0293x over previous
.Lscan1_body:
	v_add_co_u32_e32 v14, vcc, 0x15206000, v6
	s_nop 1
	v_addc_co_u32_e32 v15, vcc, 0, v7, vcc
	global_load_dword v100, v[14:15], off offset:-4096
	global_load_dword v101, v[14:15], off offset:-2048
	global_load_dword v102, v[14:15], off
	global_load_dword v103, v[14:15], off offset:2048
	v_add_co_u32_e32 v16, vcc, 0x17246000, v6
	s_nop 1
	v_addc_co_u32_e32 v17, vcc, 0, v7, vcc
	global_load_dword v104, v[16:17], off offset:-4096
	global_load_dword v105, v[16:17], off offset:-2048
	global_load_dword v106, v[16:17], off
	global_load_dword v107, v[16:17], off offset:2048
	v_add_co_u32_e32 v14, vcc, 0x15208000, v6
	s_nop 1
	v_addc_co_u32_e32 v15, vcc, 0, v7, vcc
	global_load_dword v108, v[14:15], off offset:-4096
	global_load_dword v109, v[14:15], off offset:-2048
	global_load_dword v110, v[14:15], off
	global_load_dword v111, v[14:15], off offset:2048
	v_add_co_u32_e32 v16, vcc, 0x17248000, v6
	s_nop 1
	v_addc_co_u32_e32 v17, vcc, 0, v7, vcc
	global_load_dword v112, v[16:17], off offset:-4096
	global_load_dword v113, v[16:17], off offset:-2048
	global_load_dword v114, v[16:17], off
	global_load_dword v115, v[16:17], off offset:2048
	v_add_co_u32_e32 v14, vcc, 0x1520a000, v6
	s_nop 1
	v_addc_co_u32_e32 v15, vcc, 0, v7, vcc
	global_load_dword v116, v[14:15], off offset:-4096
	global_load_dword v117, v[14:15], off offset:-2048
	global_load_dword v118, v[14:15], off
	global_load_dword v119, v[14:15], off offset:2048
	v_add_co_u32_e32 v16, vcc, 0x1724a000, v6
	s_nop 1
	v_addc_co_u32_e32 v17, vcc, 0, v7, vcc
	global_load_dword v120, v[16:17], off offset:-4096
	global_load_dword v121, v[16:17], off offset:-2048
	global_load_dword v122, v[16:17], off
	global_load_dword v123, v[16:17], off offset:2048
	v_add_co_u32_e32 v14, vcc, 0x1520c000, v6
	s_nop 1
	v_addc_co_u32_e32 v15, vcc, 0, v7, vcc
	global_load_dword v124, v[14:15], off offset:-4096
	global_load_dword v125, v[14:15], off offset:-2048
	global_load_dword v126, v[14:15], off
	global_load_dword v127, v[14:15], off offset:2048
	v_add_co_u32_e32 v16, vcc, 0x1724c000, v6
	s_nop 1
	v_addc_co_u32_e32 v17, vcc, 0, v7, vcc
	global_load_dword v128, v[16:17], off offset:-4096
	global_load_dword v129, v[16:17], off offset:-2048
	global_load_dword v130, v[16:17], off
	global_load_dword v131, v[16:17], off offset:2048
	v_add_co_u32_e32 v14, vcc, 0x1520e000, v6
	s_nop 1
	v_addc_co_u32_e32 v15, vcc, 0, v7, vcc
	global_load_dword v132, v[14:15], off offset:-4096
	global_load_dword v133, v[14:15], off offset:-2048
	global_load_dword v134, v[14:15], off
	global_load_dword v135, v[14:15], off offset:2048
	v_add_co_u32_e32 v16, vcc, 0x1724e000, v6
	s_nop 1
	v_addc_co_u32_e32 v17, vcc, 0, v7, vcc
	global_load_dword v136, v[16:17], off offset:-4096
	global_load_dword v137, v[16:17], off offset:-2048
	global_load_dword v138, v[16:17], off
	global_load_dword v139, v[16:17], off offset:2048
	v_add_co_u32_e32 v14, vcc, 0x15210000, v6
	s_nop 1
	v_addc_co_u32_e32 v15, vcc, 0, v7, vcc
	global_load_dword v140, v[14:15], off offset:-4096
	global_load_dword v141, v[14:15], off offset:-2048
	global_load_dword v142, v[14:15], off
	global_load_dword v143, v[14:15], off offset:2048
	v_add_co_u32_e32 v16, vcc, 0x17250000, v6
	s_nop 1
	v_addc_co_u32_e32 v17, vcc, 0, v7, vcc
	global_load_dword v144, v[16:17], off offset:-4096
	global_load_dword v145, v[16:17], off offset:-2048
	global_load_dword v146, v[16:17], off
	global_load_dword v147, v[16:17], off offset:2048
	v_add_co_u32_e32 v14, vcc, 0x15212000, v6
	s_nop 1
	v_addc_co_u32_e32 v15, vcc, 0, v7, vcc
	global_load_dword v148, v[14:15], off offset:-4096
	global_load_dword v149, v[14:15], off offset:-2048
	global_load_dword v150, v[14:15], off
	global_load_dword v151, v[14:15], off offset:2048
	v_add_co_u32_e32 v16, vcc, 0x17252000, v6
	s_nop 1
	v_addc_co_u32_e32 v17, vcc, 0, v7, vcc
	global_load_dword v152, v[16:17], off offset:-4096
	global_load_dword v153, v[16:17], off offset:-2048
	global_load_dword v154, v[16:17], off
	global_load_dword v155, v[16:17], off offset:2048
	s_waitcnt vmcnt(48)
	v_fmac_f32_e32 v104, v5, v100
	v_mul_f32_e32 v4, v4, v100
	v_fmac_f32_e32 v105, v104, v101
	v_mul_f32_e32 v4, v4, v101
	v_fmac_f32_e32 v106, v105, v102
	v_mul_f32_e32 v4, v4, v102
	v_fmac_f32_e32 v107, v106, v103
	v_mul_f32_e32 v4, v4, v103
	v_add_co_u32_e32 v14, vcc, 0x15214000, v6
	s_nop 1
	v_addc_co_u32_e32 v15, vcc, 0, v7, vcc
	global_load_dword v100, v[14:15], off offset:-4096
	global_load_dword v101, v[14:15], off offset:-2048
	global_load_dword v102, v[14:15], off
	global_load_dword v103, v[14:15], off offset:2048
	v_add_co_u32_e32 v16, vcc, 0x17254000, v6
	s_nop 1
	v_addc_co_u32_e32 v17, vcc, 0, v7, vcc
	global_load_dword v104, v[16:17], off offset:-4096
	global_load_dword v105, v[16:17], off offset:-2048
	global_load_dword v106, v[16:17], off
	global_load_dword v107, v[16:17], off offset:2048
	s_waitcnt vmcnt(48)
	v_fmac_f32_e32 v112, v107, v108
	v_mul_f32_e32 v4, v4, v108
	v_fmac_f32_e32 v113, v112, v109
	v_mul_f32_e32 v4, v4, v109
	v_fmac_f32_e32 v114, v113, v110
	v_mul_f32_e32 v4, v4, v110
	v_fmac_f32_e32 v115, v114, v111
	v_mul_f32_e32 v4, v4, v111
	v_add_co_u32_e32 v14, vcc, 0x15216000, v6
	s_nop 1
	v_addc_co_u32_e32 v15, vcc, 0, v7, vcc
	global_load_dword v108, v[14:15], off offset:-4096
	global_load_dword v109, v[14:15], off offset:-2048
	global_load_dword v110, v[14:15], off
	global_load_dword v111, v[14:15], off offset:2048
	v_add_co_u32_e32 v16, vcc, 0x17256000, v6
	s_nop 1
	v_addc_co_u32_e32 v17, vcc, 0, v7, vcc
	global_load_dword v112, v[16:17], off offset:-4096
	global_load_dword v113, v[16:17], off offset:-2048
	global_load_dword v114, v[16:17], off
	global_load_dword v115, v[16:17], off offset:2048
	s_waitcnt vmcnt(48)
	v_fmac_f32_e32 v120, v115, v116
	v_mul_f32_e32 v4, v4, v116
	v_fmac_f32_e32 v121, v120, v117
	v_mul_f32_e32 v4, v4, v117
	v_fmac_f32_e32 v122, v121, v118
	v_mul_f32_e32 v4, v4, v118
	v_fmac_f32_e32 v123, v122, v119
	v_mul_f32_e32 v4, v4, v119
	v_add_co_u32_e32 v14, vcc, 0x15218000, v6
	s_nop 1
	v_addc_co_u32_e32 v15, vcc, 0, v7, vcc
	global_load_dword v116, v[14:15], off offset:-4096
	global_load_dword v117, v[14:15], off offset:-2048
	global_load_dword v118, v[14:15], off
	global_load_dword v119, v[14:15], off offset:2048
	v_add_co_u32_e32 v16, vcc, 0x17258000, v6
	s_nop 1
	v_addc_co_u32_e32 v17, vcc, 0, v7, vcc
	global_load_dword v120, v[16:17], off offset:-4096
	global_load_dword v121, v[16:17], off offset:-2048
	global_load_dword v122, v[16:17], off
	global_load_dword v123, v[16:17], off offset:2048
	s_waitcnt vmcnt(48)
	v_fmac_f32_e32 v128, v123, v124
	v_mul_f32_e32 v4, v4, v124
	v_fmac_f32_e32 v129, v128, v125
	v_mul_f32_e32 v4, v4, v125
	v_fmac_f32_e32 v130, v129, v126
	v_mul_f32_e32 v4, v4, v126
	v_fmac_f32_e32 v131, v130, v127
	v_mul_f32_e32 v4, v4, v127
	v_add_co_u32_e32 v14, vcc, 0x1521a000, v6
	s_nop 1
	v_addc_co_u32_e32 v15, vcc, 0, v7, vcc
	global_load_dword v124, v[14:15], off offset:-4096
	global_load_dword v125, v[14:15], off offset:-2048
	global_load_dword v126, v[14:15], off
	global_load_dword v127, v[14:15], off offset:2048
	v_add_co_u32_e32 v16, vcc, 0x1725a000, v6
	s_nop 1
	v_addc_co_u32_e32 v17, vcc, 0, v7, vcc
	global_load_dword v128, v[16:17], off offset:-4096
	global_load_dword v129, v[16:17], off offset:-2048
	global_load_dword v130, v[16:17], off
	global_load_dword v131, v[16:17], off offset:2048
	s_waitcnt vmcnt(48)
	v_fmac_f32_e32 v136, v131, v132
	v_mul_f32_e32 v4, v4, v132
	v_fmac_f32_e32 v137, v136, v133
	v_mul_f32_e32 v4, v4, v133
	v_fmac_f32_e32 v138, v137, v134
	v_mul_f32_e32 v4, v4, v134
	v_fmac_f32_e32 v139, v138, v135
	v_mul_f32_e32 v4, v4, v135
	v_add_co_u32_e32 v14, vcc, 0x1521c000, v6
	s_nop 1
	v_addc_co_u32_e32 v15, vcc, 0, v7, vcc
	global_load_dword v132, v[14:15], off offset:-4096
	global_load_dword v133, v[14:15], off offset:-2048
	global_load_dword v134, v[14:15], off
	global_load_dword v135, v[14:15], off offset:2048
	v_add_co_u32_e32 v16, vcc, 0x1725c000, v6
	s_nop 1
	v_addc_co_u32_e32 v17, vcc, 0, v7, vcc
	global_load_dword v136, v[16:17], off offset:-4096
	global_load_dword v137, v[16:17], off offset:-2048
	global_load_dword v138, v[16:17], off
	global_load_dword v139, v[16:17], off offset:2048
	s_waitcnt vmcnt(48)
	v_fmac_f32_e32 v144, v139, v140
	v_mul_f32_e32 v4, v4, v140
	v_fmac_f32_e32 v145, v144, v141
	v_mul_f32_e32 v4, v4, v141
	v_fmac_f32_e32 v146, v145, v142
	v_mul_f32_e32 v4, v4, v142
	v_fmac_f32_e32 v147, v146, v143
	v_mul_f32_e32 v4, v4, v143
	v_add_co_u32_e32 v14, vcc, 0x1521e000, v6
	s_nop 1
	v_addc_co_u32_e32 v15, vcc, 0, v7, vcc
	global_load_dword v140, v[14:15], off offset:-4096
	global_load_dword v141, v[14:15], off offset:-2048
	global_load_dword v142, v[14:15], off
	global_load_dword v143, v[14:15], off offset:2048
	v_add_co_u32_e32 v16, vcc, 0x1725e000, v6
	s_nop 1
	v_addc_co_u32_e32 v17, vcc, 0, v7, vcc
	global_load_dword v144, v[16:17], off offset:-4096
	global_load_dword v145, v[16:17], off offset:-2048
	global_load_dword v146, v[16:17], off
	global_load_dword v147, v[16:17], off offset:2048
	s_waitcnt vmcnt(48)
	v_fmac_f32_e32 v152, v147, v148
	v_mul_f32_e32 v4, v4, v148
	v_fmac_f32_e32 v153, v152, v149
	v_mul_f32_e32 v4, v4, v149
	v_fmac_f32_e32 v154, v153, v150
	v_mul_f32_e32 v4, v4, v150
	v_fmac_f32_e32 v155, v154, v151
	v_mul_f32_e32 v4, v4, v151
	v_add_co_u32_e32 v14, vcc, 0x15220000, v6
	s_nop 1
	v_addc_co_u32_e32 v15, vcc, 0, v7, vcc
	global_load_dword v148, v[14:15], off offset:-4096
	global_load_dword v149, v[14:15], off offset:-2048
	global_load_dword v150, v[14:15], off
	global_load_dword v151, v[14:15], off offset:2048
	v_add_co_u32_e32 v16, vcc, 0x17260000, v6
	s_nop 1
	v_addc_co_u32_e32 v17, vcc, 0, v7, vcc
	global_load_dword v152, v[16:17], off offset:-4096
	global_load_dword v153, v[16:17], off offset:-2048
	global_load_dword v154, v[16:17], off
	global_load_dword v155, v[16:17], off offset:2048
	s_waitcnt vmcnt(48)
	v_fmac_f32_e32 v104, v155, v100
	v_mul_f32_e32 v4, v4, v100
	v_fmac_f32_e32 v105, v104, v101
	v_mul_f32_e32 v4, v4, v101
	v_fmac_f32_e32 v106, v105, v102
	v_mul_f32_e32 v4, v4, v102
	v_fmac_f32_e32 v107, v106, v103
	v_mul_f32_e32 v4, v4, v103
	v_add_co_u32_e32 v14, vcc, 0x15222000, v6
	s_nop 1
	v_addc_co_u32_e32 v15, vcc, 0, v7, vcc
	global_load_dword v100, v[14:15], off offset:-4096
	global_load_dword v101, v[14:15], off offset:-2048
	global_load_dword v102, v[14:15], off
	global_load_dword v103, v[14:15], off offset:2048
	v_add_co_u32_e32 v16, vcc, 0x17262000, v6
	s_nop 1
	v_addc_co_u32_e32 v17, vcc, 0, v7, vcc
	global_load_dword v104, v[16:17], off offset:-4096
	global_load_dword v105, v[16:17], off offset:-2048
	global_load_dword v106, v[16:17], off
	global_load_dword v107, v[16:17], off offset:2048
	s_waitcnt vmcnt(48)
	v_fmac_f32_e32 v112, v107, v108
	v_mul_f32_e32 v4, v4, v108
	v_fmac_f32_e32 v113, v112, v109
	v_mul_f32_e32 v4, v4, v109
	v_fmac_f32_e32 v114, v113, v110
	v_mul_f32_e32 v4, v4, v110
	v_fmac_f32_e32 v115, v114, v111
	v_mul_f32_e32 v4, v4, v111
	v_add_co_u32_e32 v14, vcc, 0x15224000, v6
	s_nop 1
	v_addc_co_u32_e32 v15, vcc, 0, v7, vcc
	global_load_dword v108, v[14:15], off offset:-4096
	global_load_dword v109, v[14:15], off offset:-2048
	global_load_dword v110, v[14:15], off
	global_load_dword v111, v[14:15], off offset:2048
	v_add_co_u32_e32 v16, vcc, 0x17264000, v6
	s_nop 1
	v_addc_co_u32_e32 v17, vcc, 0, v7, vcc
	global_load_dword v112, v[16:17], off offset:-4096
	global_load_dword v113, v[16:17], off offset:-2048
	global_load_dword v114, v[16:17], off
	global_load_dword v115, v[16:17], off offset:2048
	s_waitcnt vmcnt(48)
	v_fmac_f32_e32 v120, v115, v116
	v_mul_f32_e32 v4, v4, v116
	v_fmac_f32_e32 v121, v120, v117
	v_mul_f32_e32 v4, v4, v117
	v_fmac_f32_e32 v122, v121, v118
	v_mul_f32_e32 v4, v4, v118
	v_fmac_f32_e32 v123, v122, v119
	v_mul_f32_e32 v4, v4, v119
	s_waitcnt vmcnt(40)
	v_fmac_f32_e32 v128, v123, v124
	v_mul_f32_e32 v4, v4, v124
	v_fmac_f32_e32 v129, v128, v125
	v_mul_f32_e32 v4, v4, v125
	v_fmac_f32_e32 v130, v129, v126
	v_mul_f32_e32 v4, v4, v126
	v_fmac_f32_e32 v131, v130, v127
	v_mul_f32_e32 v4, v4, v127
	s_waitcnt vmcnt(32)
	v_fmac_f32_e32 v136, v131, v132
	v_mul_f32_e32 v4, v4, v132
	v_fmac_f32_e32 v137, v136, v133
	v_mul_f32_e32 v4, v4, v133
	v_fmac_f32_e32 v138, v137, v134
	v_mul_f32_e32 v4, v4, v134
	v_fmac_f32_e32 v139, v138, v135
	v_mul_f32_e32 v4, v4, v135
	s_waitcnt vmcnt(24)
	v_fmac_f32_e32 v144, v139, v140
	v_mul_f32_e32 v4, v4, v140
	v_fmac_f32_e32 v145, v144, v141
	v_mul_f32_e32 v4, v4, v141
	v_fmac_f32_e32 v146, v145, v142
	v_mul_f32_e32 v4, v4, v142
	v_fmac_f32_e32 v147, v146, v143
	v_mul_f32_e32 v4, v4, v143
	s_waitcnt vmcnt(16)
	v_fmac_f32_e32 v152, v147, v148
	v_mul_f32_e32 v4, v4, v148
	v_fmac_f32_e32 v153, v152, v149
	v_mul_f32_e32 v4, v4, v149
	v_fmac_f32_e32 v154, v153, v150
	v_mul_f32_e32 v4, v4, v150
	v_fmac_f32_e32 v155, v154, v151
	v_mul_f32_e32 v4, v4, v151
	s_waitcnt vmcnt(8)
	v_fmac_f32_e32 v104, v155, v100
	v_mul_f32_e32 v4, v4, v100
	v_fmac_f32_e32 v105, v104, v101
	v_mul_f32_e32 v4, v4, v101
	v_fmac_f32_e32 v106, v105, v102
	v_mul_f32_e32 v4, v4, v102
	v_fmac_f32_e32 v107, v106, v103
	v_mul_f32_e32 v4, v4, v103
	s_waitcnt vmcnt(0)
	v_fmac_f32_e32 v112, v107, v108
	v_mul_f32_e32 v4, v4, v108
	v_fmac_f32_e32 v113, v112, v109
	v_mul_f32_e32 v4, v4, v109
	v_fmac_f32_e32 v114, v113, v110
	v_mul_f32_e32 v4, v4, v110
	v_fmac_f32_e32 v115, v114, v111
	v_mul_f32_e32 v4, v4, v111
	v_mov_b32_e32 v5, v115
	v_readlane_b32 s8, v254, 36
	v_lshlrev_b32_e32 v0, 12, v12
	v_readlane_b32 s9, v254, 37
	s_andn2_b64 s[4:5], s[4:5], exec
	s_nop 0
	v_lshl_add_u64 v[6:7], s[8:9], 0, v[0:1]
	v_lshl_add_u64 v[6:7], v[2:3], 3, v[6:7]
	global_store_dwordx2 v[6:7], v[4:5], off

.LBB0_327:
	s_or_b64 exec, exec, s[4:5]
	v_readlane_b32 s4, v254, 44
	v_readlane_b32 s5, v254, 45
	v_mov_b32_e32 v11, 0x800
	v_mov_b64_e32 v[146:147], 0x200
	v_mov_b32_e32 v0, 0x840
	v_mov_b32_e32 v9, 0x810
	s_nop 0
	global_load_dwordx2 v[140:141], v1, s[4:5] offset:1024
	s_mov_b64 s[4:5], exec
	v_readlane_b32 s6, v254, 50
	v_readlane_b32 s7, v254, 51
	s_and_b64 s[6:7], s[4:5], s[6:7]
	s_mov_b64 exec, s[6:7]
	v_mov_b64_e32 v[146:147], 0x1c00
	v_mov_b32_e32 v9, 0x1000
	v_mov_b32_e32 v0, 0x1000
	v_mov_b32_e32 v11, v12
	s_or_b64 exec, exec, s[4:5]
	v_lshlrev_b32_e32 v12, 4, v2
	v_and_b32_e32 v21, 0x70, v12
	v_add3_u32 v12, v8, v11, -1
	v_and_b32_e32 v12, 0xffffffc0, v12
	v_add_u32_e32 v12, 64, v12
	v_min_u32_e32 v12, v9, v12
	v_add_u32_e32 v22, 63, v12
	v_ashrrev_i32_e32 v20, 3, v2
	v_lshrrev_b32_e32 v15, 6, v22
	v_lshlrev_b32_e32 v142, 1, v13
	v_lshlrev_b32_e32 v13, 1, v20
	v_add_u32_e32 v148, -1, v15
	v_mov_b32_e32 v149, v1
	v_mov_b32_e32 v143, v1
	v_mul_lo_u32 v0, v0, v13
	v_mad_u64_u32 v[16:17], s[4:5], v148, v146, 0
	v_lshlrev_b64 v[18:19], 7, v[148:149]
	v_lshl_add_u64 v[6:7], v[6:7], 0, v[142:143]
	v_mul_lo_u32 v12, v13, v146
	v_or_b32_e32 v14, v0, v21
	v_lshlrev_b64 v[16:17], 7, v[16:17]
	v_lshl_add_u64 v[18:19], v[4:5], 0, v[18:19]
	v_mov_b32_e32 v15, v1
	v_or_b32_e32 v12, v12, v21
	v_lshl_add_u64 v[16:17], v[6:7], 0, v[16:17]
	v_mov_b32_e32 v13, v1
	v_lshl_add_u64 v[18:19], v[18:19], 0, v[14:15]
	v_readlane_b32 s4, v254, 16
	v_lshl_add_u64 v[16:17], v[16:17], 0, v[12:13]
	global_load_dwordx4 v[116:119], v[18:19], off
	global_load_dwordx4 v[112:115], v[16:17], off
	v_readlane_b32 s5, v254, 17
	v_ashrrev_i32_e32 v19, 1, v2
	s_movk_i32 s0, 0xffe0
	v_mov_b64_e32 v[16:17], s[4:5]
	v_bfi_b32 v149, s0, v19, v2
	v_add_u32_e32 v0, 1, v10
	v_bfe_u32 v18, v2, 5, 1
	v_mad_u64_u32 v[144:145], s[4:5], v3, s96, v[16:17]
	s_movk_i32 s10, 0x90
	v_cmp_lt_i32_e64 s[6:7], v149, v8
	v_and_b32_e32 v10, 31, v2
	v_cvt_f32_ubyte0_e32 v16, v0
	v_lshlrev_b32_e32 v0, 4, v18
	v_lshlrev_b32_e32 v147, 2, v18
	v_mul_lo_u32 v18, v20, s10
	v_lshl_add_u64 v[2:3], v[144:145], 0, v[142:143]
	v_cndmask_b32_e64 v20, 0, v149, s[6:7]
	v_mad_i64_i32 v[2:3], s[4:5], v20, s96, v[2:3]
	v_lshl_add_u64 v[2:3], v[2:3], 0, v[0:1]
	global_load_dwordx4 v[120:123], v[2:3], off offset:2048
	global_load_dwordx4 v[124:127], v[2:3], off offset:2080
	global_load_dwordx4 v[128:131], v[2:3], off offset:2112
	global_load_dwordx4 v[132:135], v[2:3], off offset:2144
	s_mov_b32 s0, 0x42fc0000
	v_and_b32_e32 v17, 0xffffffe0, v19
	v_cmp_lt_f32_e32 vcc, s0, v16
	v_mov_b32_e32 v19, 0x42800000
	v_add_u32_e32 v11, v11, v17
	v_cndmask_b32_e32 v19, 0, v19, vcc
	v_sub_f32_e32 v16, v19, v16
	v_ashrrev_i32_e32 v3, 31, v11
	v_exp_f32_e32 v16, v16
	v_lshrrev_b32_e32 v3, 26, v3
	v_add_u32_e32 v3, v11, v3
	v_add3_u32 v143, 0, v18, v21
	v_not_b32_e32 v2, 63
	v_or_b32_e32 v18, v11, v10
	v_and_b32_e32 v3, 0xffffffc0, v3
	v_cndmask_b32_e32 v2, 0, v2, vcc
	v_cvt_f32_i32_e32 v175, v18
	v_add_u32_e32 v3, 64, v3
	v_lshl_add_u64 v[152:153], v[4:5], 0, v[14:15]
	v_and_b32_e32 v4, 1, v148
	v_ldexp_f32 v2, v16, v2
	v_min_i32_e32 v178, v9, v3
	v_cmp_eq_u32_e32 vcc, 1, v4
	v_mul_f32_e32 v154, 0x3fb8aa3b, v2
	v_add_u32_e32 v2, 63, v178
	v_cvt_f32_ubyte0_e32 v23, v147
	v_cndmask_b32_e32 v4, 0, v208, vcc
	v_ashrrev_i32_e32 v2, 6, v2
	v_cmp_lt_i32_e64 s[40:41], v17, v8
	v_mad_u32_u24 v0, v10, s10, v0
	s_add_i32 s0, 0, 0x1200
	v_sub_f32_e32 v3, v23, v175
	v_add_u32_e32 v4, v143, v4
	v_cndmask_b32_e64 v182, 0, v2, s[40:41]
	v_add_u32_e32 v184, s0, v0
	v_and_b32_e32 v2, 0x3fc0, v22
	v_readlane_b32 s0, v254, 2
	v_mov_b32_e32 v14, v1
	v_lshl_add_u64 v[150:151], v[6:7], 0, v[12:13]
	v_mul_f32_e32 v180, v154, v3
	v_xor_b32_e32 v156, 0x80000000, v154
	s_waitcnt vmcnt(5)
	ds_write_b128 v4, v[116:119] offset:9216
	s_waitcnt vmcnt(4)
	ds_write_b128 v4, v[112:115]
	v_or_b32_e32 v185, v2, v147
	v_add_u32_e32 v186, s0, v0
	v_subrev_u32_e32 v187, 32, v2
	v_mov_b32_e32 v0, v1
	v_mov_b32_e32 v2, v1
	v_mov_b32_e32 v3, v1
	v_mov_b32_e32 v4, v1
	v_mov_b32_e32 v5, v1
	v_mov_b32_e32 v6, v1
	v_mov_b32_e32 v7, v1
	v_mov_b32_e32 v8, v1
	v_mov_b32_e32 v9, v1
	v_mov_b32_e32 v10, v1
	v_mov_b32_e32 v11, v1
	v_mov_b32_e32 v12, v1
	v_mov_b64_e32 v[62:63], v[14:15]
	v_mov_b64_e32 v[30:31], v[14:15]
	v_mov_b64_e32 v[78:79], v[14:15]
	v_mov_b64_e32 v[46:47], v[14:15]
	v_subrev_u32_e32 v179, 64, v178
	v_add_u32_e32 v183, -1, v182
	v_mov_b32_e32 v157, v156
	v_mov_b32_e32 v158, v156
	v_mov_b32_e32 v159, v156
	v_mov_b32_e32 v160, v156
	v_mov_b32_e32 v161, v156
	v_mov_b32_e32 v162, v156
	v_mov_b32_e32 v163, v156
	v_mov_b32_e32 v164, v156
	v_mov_b32_e32 v165, v156
	v_mov_b32_e32 v166, v156
	v_mov_b32_e32 v167, v156
	v_mov_b32_e32 v168, v156
	v_mov_b32_e32 v169, v156
	v_mov_b32_e32 v176, v156
	v_mov_b32_e32 v177, v156
	v_mov_b32_e32 v155, v154
	v_mov_b32_e32 v190, 0xf149f2ca
	v_mov_b32_e32 v188, 0
	s_mov_b64 s[10:11], 0
	v_mov_b32_e32 v181, 0
	v_mov_b32_e32 v191, 0xf149f2ca
	v_mov_b64_e32 v[60:61], v[12:13]
	v_mov_b64_e32 v[58:59], v[10:11]
	v_mov_b64_e32 v[56:57], v[8:9]
	v_mov_b64_e32 v[54:55], v[6:7]
	v_mov_b64_e32 v[52:53], v[4:5]
	v_mov_b64_e32 v[50:51], v[2:3]
	v_mov_b64_e32 v[48:49], v[0:1]
	v_mov_b64_e32 v[28:29], v[12:13]
	v_mov_b64_e32 v[26:27], v[10:11]
	v_mov_b64_e32 v[24:25], v[8:9]
	v_mov_b64_e32 v[22:23], v[6:7]
	v_mov_b64_e32 v[20:21], v[4:5]
	v_mov_b64_e32 v[18:19], v[2:3]
	v_mov_b64_e32 v[16:17], v[0:1]
	v_mov_b64_e32 v[76:77], v[12:13]
	v_mov_b64_e32 v[74:75], v[10:11]
	v_mov_b64_e32 v[72:73], v[8:9]
	v_mov_b64_e32 v[70:71], v[6:7]
	v_mov_b64_e32 v[68:69], v[4:5]
	v_mov_b64_e32 v[66:67], v[2:3]
	v_mov_b64_e32 v[64:65], v[0:1]
	v_mov_b64_e32 v[44:45], v[12:13]
	v_mov_b64_e32 v[42:43], v[10:11]
	v_mov_b64_e32 v[40:41], v[8:9]
	v_mov_b64_e32 v[38:39], v[6:7]
	v_mov_b64_e32 v[36:37], v[4:5]
	v_mov_b64_e32 v[34:35], v[2:3]
	v_mov_b64_e32 v[32:33], v[0:1]
	s_waitcnt vmcnt(0) lgkmcnt(0)
	s_barrier
	s_branch .LBB0_331

.LBB0_337:
	ds_read_b128 v[80:83], v0
	ds_read_b128 v[96:99], v138
	ds_read_b128 v[2:5], v138 offset:32
	v_add_u32_e32 v174, s0, v185
	ds_read_b128 v[10:13], v138 offset:4608
	ds_read_b128 v[6:9], v138 offset:4640
	ds_read_b128 v[100:103], v0 offset:32
	s_waitcnt lgkmcnt(5)
	v_mfma_f32_32x32x16_bf16 v[80:95], v[80:83], v[120:123], 0
	v_subrev_u32_e32 v139, 32, v174
	v_cvt_f32_u32_e32 v14, v139
	v_subrev_u32_e32 v232, 31, v174
	v_subrev_u32_e32 v231, 30, v174
	v_subrev_u32_e32 v230, 29, v174
	v_sub_f32_e32 v104, v14, v175
	v_add_f32_e32 v105, 1.0, v104
	s_waitcnt lgkmcnt(0)
	v_mfma_f32_32x32x16_bf16 v[80:95], v[100:103], v[124:127], v[80:95]
	v_add_f32_e64 v106, v104, s2
	v_add_f32_e64 v107, v104, s3
	v_add_f32_e64 v102, v104, s36
	v_add_f32_e64 v103, v104, s37
	v_and_b32_e32 v101, 0x7fffffff, v107
	v_and_b32_e32 v100, 0x7fffffff, v106
	v_and_b32_e32 v107, 0x7fffffff, v103
	v_and_b32_e32 v106, 0x7fffffff, v102
	v_pk_add_f32 v[102:103], v[104:105], s[28:29] op_sel_hi:[0,1]
	v_and_b32_e32 v109, 0x7fffffff, v103
	v_and_b32_e32 v108, 0x7fffffff, v102
	v_pk_add_f32 v[102:103], v[104:105], s[38:39] op_sel_hi:[0,1]
	v_pk_add_f32 v[172:173], v[104:105], s[34:35] op_sel_hi:[0,1]
	v_pk_add_f32 v[14:15], v[104:105], s[30:31] op_sel_hi:[0,1]
	v_and_b32_e32 v111, 0x7fffffff, v103
	v_and_b32_e32 v110, 0x7fffffff, v102
	v_pk_add_f32 v[102:103], v[104:105], s[20:21] op_sel_hi:[0,1]
	v_and_b32_e32 v15, 0x7fffffff, v15
	v_and_b32_e32 v14, 0x7fffffff, v14
	v_and_b32_e32 v137, 0x7fffffff, v103
	v_and_b32_e32 v136, 0x7fffffff, v102
	v_and_b32_e32 v103, 0x7fffffff, v173
	v_and_b32_e32 v102, 0x7fffffff, v172
	v_and_b32_e32 v104, 0x7fffffff, v104
	v_and_b32_e32 v105, 0x7fffffff, v105
	v_pk_fma_f32 v[94:95], v[176:177], v[136:137], v[94:95]
	v_pk_fma_f32 v[92:93], v[168:169], v[110:111], v[92:93]
	v_pk_fma_f32 v[90:91], v[166:167], v[108:109], v[90:91]
	v_pk_fma_f32 v[88:89], v[164:165], v[106:107], v[88:89]
	v_pk_fma_f32 v[86:87], v[162:163], v[100:101], v[86:87]
	v_pk_fma_f32 v[84:85], v[160:161], v[14:15], v[84:85]
	v_pk_fma_f32 v[82:83], v[158:159], v[102:103], v[82:83]
	v_pk_fma_f32 v[80:81], v[156:157], v[104:105], v[80:81]
	v_subrev_u32_e32 v229, 24, v174
	v_subrev_u32_e32 v228, 23, v174
	v_subrev_u32_e32 v227, 22, v174
	v_subrev_u32_e32 v226, 21, v174
	v_add_u32_e32 v199, -16, v174
	v_add_u32_e32 v198, -15, v174
	v_add_u32_e32 v197, -14, v174
	v_add_u32_e32 v196, -13, v174
	v_add_u32_e32 v195, -8, v174
	v_add_u32_e32 v194, -7, v174
	v_add_u32_e32 v193, -6, v174
	v_add_u32_e32 v192, -5, v174
	s_and_saveexec_b64 s[16:17], s[4:5]
	s_cbranch_execz .LBB0_339
	v_cmp_lt_i32_e32 vcc, v139, v178
	s_nop 1
	v_cndmask_b32_e32 v80, v209, v80, vcc
	v_cmp_lt_i32_e32 vcc, v232, v178
	s_nop 1
	v_cndmask_b32_e32 v81, v209, v81, vcc
	v_cmp_lt_i32_e32 vcc, v231, v178
	s_nop 1
	v_cndmask_b32_e32 v82, v209, v82, vcc
	v_cmp_lt_i32_e32 vcc, v230, v178
	s_nop 1
	v_cndmask_b32_e32 v83, v209, v83, vcc
	v_cmp_lt_i32_e32 vcc, v229, v178
	s_nop 1
	v_cndmask_b32_e32 v84, v209, v84, vcc
	v_cmp_lt_i32_e32 vcc, v228, v178
	s_nop 1
	v_cndmask_b32_e32 v85, v209, v85, vcc
	v_cmp_lt_i32_e32 vcc, v227, v178
	s_nop 1
	v_cndmask_b32_e32 v86, v209, v86, vcc
	v_cmp_lt_i32_e32 vcc, v226, v178
	s_nop 1
	v_cndmask_b32_e32 v87, v209, v87, vcc
	v_cmp_lt_i32_e32 vcc, v199, v178
	s_nop 1
	v_cndmask_b32_e32 v88, v209, v88, vcc
	v_cmp_lt_i32_e32 vcc, v198, v178
	s_nop 1
	v_cndmask_b32_e32 v89, v209, v89, vcc
	v_cmp_lt_i32_e32 vcc, v197, v178
	s_nop 1
	v_cndmask_b32_e32 v90, v209, v90, vcc
	v_cmp_lt_i32_e32 vcc, v196, v178
	s_nop 1
	v_cndmask_b32_e32 v91, v209, v91, vcc
	v_cmp_lt_i32_e32 vcc, v195, v178
	s_nop 1
	v_cndmask_b32_e32 v92, v209, v92, vcc
	v_cmp_lt_i32_e32 vcc, v194, v178
	s_nop 1
	v_cndmask_b32_e32 v93, v209, v93, vcc
	v_cmp_lt_i32_e32 vcc, v193, v178
	s_nop 1
	v_cndmask_b32_e32 v94, v209, v94, vcc
	v_cmp_lt_i32_e32 vcc, v192, v178
	s_nop 1
	v_cndmask_b32_e32 v95, v209, v95, vcc

.LBB0_341:
	v_sub_f32_e32 v80, v80, v190
	v_exp_f32_e32 v233, v80
	v_sub_f32_e32 v80, v81, v190
	v_exp_f32_e32 v234, v80
	v_sub_f32_e32 v80, v82, v190
	v_exp_f32_e32 v235, v80
	v_sub_f32_e32 v80, v83, v190
	v_exp_f32_e32 v236, v80
	v_sub_f32_e32 v80, v84, v190
	v_exp_f32_e32 v237, v80
	v_sub_f32_e32 v80, v85, v190
	v_exp_f32_e32 v238, v80
	v_sub_f32_e32 v80, v86, v190
	v_exp_f32_e32 v239, v80
	v_sub_f32_e32 v80, v87, v190
	v_exp_f32_e32 v240, v80
	v_sub_f32_e32 v80, v88, v190
	v_exp_f32_e32 v241, v80
	v_sub_f32_e32 v80, v89, v190
	v_exp_f32_e32 v243, v80
	v_sub_f32_e32 v80, v90, v190
	v_exp_f32_e32 v244, v80
	v_sub_f32_e32 v80, v91, v190
	v_exp_f32_e32 v245, v80
	v_sub_f32_e32 v80, v92, v190
	v_exp_f32_e32 v246, v80
	v_sub_f32_e32 v80, v93, v190
	v_exp_f32_e32 v247, v80
	v_sub_f32_e32 v80, v94, v190
	v_exp_f32_e32 v248, v80
	v_sub_f32_e32 v80, v95, v190
	v_exp_f32_e32 v242, v80
	v_cvt_pk_bf16_f32 v80, v233, v234
	v_cvt_pk_bf16_f32 v81, v235, v236
	v_cvt_pk_bf16_f32 v82, v237, v238
	v_cvt_pk_bf16_f32 v83, v239, v240
	s_nop 1
	v_mfma_f32_32x32x16_bf16 v[48:63], v[96:99], v[80:83], v[48:63]
	v_mfma_f32_32x32x16_bf16 v[16:31], v[10:13], v[80:83], v[16:31]
	v_cvt_pk_bf16_f32 v80, v241, v243
	v_cvt_pk_bf16_f32 v81, v244, v245
	v_cvt_pk_bf16_f32 v82, v246, v247
	v_cvt_pk_bf16_f32 v83, v248, v242
	s_nop 1
	v_mfma_f32_32x32x16_bf16 v[48:63], v[2:5], v[80:83], v[48:63]
	v_mfma_f32_32x32x16_bf16 v[16:31], v[6:9], v[80:83], v[16:31]
	ds_read_b128 v[80:83], v0 offset:64
	ds_read_b128 v[202:205], v0 offset:96
	s_waitcnt lgkmcnt(1)
	v_mfma_f32_32x32x16_bf16 v[80:95], v[80:83], v[128:131], 0
	s_waitcnt lgkmcnt(0)
	v_mfma_f32_32x32x16_bf16 v[80:95], v[202:205], v[132:135], v[80:95]
	s_nop 11
	v_pk_fma_f32 v[94:95], v[176:177], v[136:137], v[94:95]
	v_pk_fma_f32 v[92:93], v[168:169], v[110:111], v[92:93]
	v_pk_fma_f32 v[90:91], v[166:167], v[108:109], v[90:91]
	v_pk_fma_f32 v[88:89], v[164:165], v[106:107], v[88:89]
	v_pk_fma_f32 v[86:87], v[162:163], v[100:101], v[86:87]
	v_pk_fma_f32 v[14:15], v[160:161], v[14:15], v[84:85]
	v_pk_fma_f32 v[82:83], v[158:159], v[102:103], v[82:83]
	v_pk_fma_f32 v[80:81], v[156:157], v[104:105], v[80:81]
	s_and_saveexec_b64 s[16:17], s[4:5]
	s_cbranch_execz .LBB0_343
	v_cmp_lt_i32_e32 vcc, v139, v178
	s_nop 1
	v_cndmask_b32_e32 v80, v209, v80, vcc
	v_cmp_lt_i32_e32 vcc, v232, v178
	s_nop 1
	v_cndmask_b32_e32 v81, v209, v81, vcc
	v_cmp_lt_i32_e32 vcc, v231, v178
	s_nop 1
	v_cndmask_b32_e32 v82, v209, v82, vcc
	v_cmp_lt_i32_e32 vcc, v230, v178
	s_nop 1
	v_cndmask_b32_e32 v83, v209, v83, vcc
	v_cmp_lt_i32_e32 vcc, v229, v178
	s_nop 1
	v_cndmask_b32_e32 v14, v209, v14, vcc
	v_cmp_lt_i32_e32 vcc, v228, v178
	s_nop 1
	v_cndmask_b32_e32 v15, v209, v15, vcc
	v_cmp_lt_i32_e32 vcc, v227, v178
	s_nop 1
	v_cndmask_b32_e32 v86, v209, v86, vcc
	v_cmp_lt_i32_e32 vcc, v226, v178
	s_nop 1
	v_cndmask_b32_e32 v87, v209, v87, vcc
	v_cmp_lt_i32_e32 vcc, v199, v178
	s_nop 1
	v_cndmask_b32_e32 v88, v209, v88, vcc
	v_cmp_lt_i32_e32 vcc, v198, v178
	s_nop 1
	v_cndmask_b32_e32 v89, v209, v89, vcc
	v_cmp_lt_i32_e32 vcc, v197, v178
	s_nop 1
	v_cndmask_b32_e32 v90, v209, v90, vcc
	v_cmp_lt_i32_e32 vcc, v196, v178
	s_nop 1
	v_cndmask_b32_e32 v91, v209, v91, vcc
	v_cmp_lt_i32_e32 vcc, v195, v178
	s_nop 1
	v_cndmask_b32_e32 v92, v209, v92, vcc
	v_cmp_lt_i32_e32 vcc, v194, v178
	s_nop 1
	v_cndmask_b32_e32 v93, v209, v93, vcc
	v_cmp_lt_i32_e32 vcc, v193, v178
	s_nop 1
	v_cndmask_b32_e32 v94, v209, v94, vcc
	v_cmp_lt_i32_e32 vcc, v192, v178
	s_nop 1
	v_cndmask_b32_e32 v95, v209, v95, vcc

.LBB0_349:
	ds_read_b128 v[196:199], v0
	v_cvt_f32_u32_e32 v80, v15
	v_add_u32_e32 v2, s0, v14
	ds_read_b128 v[202:205], v0 offset:32
	ds_read_b128 v[136:139], v2
	v_fma_f32 v81, v154, v80, v180
	v_sub_f32_e32 v80, v81, v190
	v_fma_f32 v96, 0, v154, v80
	v_add_f32_e32 v97, v154, v80
	v_pk_fma_f32 v[98:99], v[154:155], s[34:35], v[80:81] op_sel_hi:[1,1,0]
	v_pk_fma_f32 v[100:101], v[154:155], s[30:31], v[80:81] op_sel_hi:[1,1,0]
	v_pk_fma_f32 v[102:103], v[154:155], s[2:3], v[80:81] op_sel_hi:[1,1,0]
	v_pk_fma_f32 v[104:105], v[154:155], s[36:37], v[80:81] op_sel_hi:[1,1,0]
	v_pk_fma_f32 v[106:107], v[154:155], s[28:29], v[80:81] op_sel_hi:[1,1,0]
	v_pk_fma_f32 v[108:109], v[154:155], s[38:39], v[80:81] op_sel_hi:[1,1,0]
	v_pk_fma_f32 v[110:111], v[154:155], s[20:21], v[80:81] op_sel_hi:[1,1,0]
	ds_read_b128 v[6:9], v2 offset:32
	ds_read_b128 v[10:13], v2 offset:4608
	ds_read_b128 v[2:5], v2 offset:4640
	ds_read_b128 v[192:195], v0 offset:64
	ds_read_b128 v[212:215], v0 offset:96
	s_waitcnt lgkmcnt(7)
	v_mfma_f32_32x32x16_bf16 v[96:111], v[196:199], v[120:123], v[96:111]
	v_sub_f32_e32 v94, v81, v191
	v_fma_f32 v80, 0, v154, v94
	v_add_f32_e32 v81, v154, v94
	v_fma_f32 v82, v154, s34, v94
	v_fma_f32 v83, v155, s35, v94
	v_pk_fma_f32 v[84:85], v[154:155], s[30:31], v[94:95] op_sel_hi:[1,1,0]
	v_pk_fma_f32 v[86:87], v[154:155], s[2:3], v[94:95] op_sel_hi:[1,1,0]
	v_pk_fma_f32 v[88:89], v[154:155], s[36:37], v[94:95] op_sel_hi:[1,1,0]
	s_waitcnt lgkmcnt(6)
	v_mfma_f32_32x32x16_bf16 v[96:111], v[202:205], v[124:127], v[96:111]
	v_fma_f32 v90, v154, s28, v94
	v_fma_f32 v91, v155, s29, v94
	v_fma_f32 v92, v154, s38, v94
	v_fma_f32 v93, v155, s39, v94
	v_pk_fma_f32 v[94:95], v[154:155], s[20:21], v[94:95] op_sel_hi:[1,1,0]
	s_waitcnt lgkmcnt(1)
	s_nop 0
	v_mfma_f32_32x32x16_bf16 v[80:95], v[192:195], v[128:131], v[80:95]
	s_nop 3
	v_max_f32_e32 v172, v97, v97
	v_max_f32_e32 v173, v96, v96
	v_max_f32_e32 v172, v173, v172
	v_max3_f32 v172, v172, v98, v99
	v_max3_f32 v172, v172, v100, v101
	v_max3_f32 v172, v172, v102, v103
	v_max3_f32 v172, v172, v104, v105
	s_waitcnt lgkmcnt(0)
	v_mfma_f32_32x32x16_bf16 v[80:95], v[212:215], v[132:135], v[80:95]
	v_max3_f32 v172, v172, v106, v107
	v_max3_f32 v172, v172, v108, v109
	v_max3_f32 v192, v172, v110, v111
	v_cmp_lt_f32_e32 vcc, s30, v192
	s_cbranch_vccz .LBB0_351
	v_and_b32_e32 v173, 64, v210
	v_xor_b32_e32 v172, 32, v210
	v_add_u32_e32 v173, 64, v173
	v_cmp_lt_i32_e32 vcc, v172, v173
	s_nop 1
	v_cndmask_b32_e32 v172, v210, v172, vcc
	v_lshlrev_b32_e32 v172, 2, v172
	ds_bpermute_b32 v172, v172, v192
	s_waitcnt lgkmcnt(0)
	v_max3_f32 v172, v192, v172, 0
	v_exp_f32_e64 v174, -v172
	v_add_f32_e32 v190, v190, v172
	v_pk_add_f32 v[96:97], v[96:97], v[172:173] op_sel_hi:[1,0] neg_lo:[0,1] neg_hi:[0,1]
	v_pk_add_f32 v[98:99], v[98:99], v[172:173] op_sel_hi:[1,0] neg_lo:[0,1] neg_hi:[0,1]
	v_mul_f32_e32 v188, v188, v174
	v_pk_mul_f32 v[62:63], v[62:63], v[174:175] op_sel_hi:[1,0]
	v_pk_mul_f32 v[60:61], v[60:61], v[174:175] op_sel_hi:[1,0]
	v_pk_mul_f32 v[58:59], v[58:59], v[174:175] op_sel_hi:[1,0]
	v_pk_mul_f32 v[56:57], v[56:57], v[174:175] op_sel_hi:[1,0]
	v_pk_mul_f32 v[54:55], v[54:55], v[174:175] op_sel_hi:[1,0]
	v_pk_mul_f32 v[52:53], v[52:53], v[174:175] op_sel_hi:[1,0]
	v_pk_mul_f32 v[50:51], v[50:51], v[174:175] op_sel_hi:[1,0]
	v_pk_mul_f32 v[48:49], v[48:49], v[174:175] op_sel_hi:[1,0]
	v_pk_mul_f32 v[30:31], v[30:31], v[174:175] op_sel_hi:[1,0]
	v_pk_mul_f32 v[28:29], v[28:29], v[174:175] op_sel_hi:[1,0]
	v_pk_mul_f32 v[26:27], v[26:27], v[174:175] op_sel_hi:[1,0]
	v_pk_mul_f32 v[24:25], v[24:25], v[174:175] op_sel_hi:[1,0]
	v_pk_mul_f32 v[22:23], v[22:23], v[174:175] op_sel_hi:[1,0]
	v_pk_mul_f32 v[20:21], v[20:21], v[174:175] op_sel_hi:[1,0]
	v_pk_mul_f32 v[18:19], v[18:19], v[174:175] op_sel_hi:[1,0]
	v_pk_mul_f32 v[16:17], v[16:17], v[174:175] op_sel_hi:[1,0]
	v_pk_add_f32 v[100:101], v[100:101], v[172:173] op_sel_hi:[1,0] neg_lo:[0,1] neg_hi:[0,1]
	v_pk_add_f32 v[102:103], v[102:103], v[172:173] op_sel_hi:[1,0] neg_lo:[0,1] neg_hi:[0,1]
	v_pk_add_f32 v[104:105], v[104:105], v[172:173] op_sel_hi:[1,0] neg_lo:[0,1] neg_hi:[0,1]
	v_pk_add_f32 v[106:107], v[106:107], v[172:173] op_sel_hi:[1,0] neg_lo:[0,1] neg_hi:[0,1]
	v_pk_add_f32 v[108:109], v[108:109], v[172:173] op_sel_hi:[1,0] neg_lo:[0,1] neg_hi:[0,1]
	v_pk_add_f32 v[110:111], v[110:111], v[172:173] op_sel_hi:[1,0] neg_lo:[0,1] neg_hi:[0,1]
